# overlap HGRN recurrence with the HGRN input-projection GEMM: 64 recurrence workgroups skip the GEMM and wait on per-row-group counters; GEMM runs on 192 workgroups with time-ordered tiles
# speedup vs baseline: 1.0181x; 1.0181x over previous
.LBB0_122:
	s_or_b64 exec, exec, s[0:1]
	s_cmpk_lt_u32 s3, 64
	s_cbranch_scc1 .Lovl_skip_p1
	v_mov_b32_e32 v8, v208
	s_cmpk_lt_i32 s3, 0x1010
	s_waitcnt lgkmcnt(0)
	s_barrier
	s_cselect_b64 s[0:1], -1, 0
	s_cmpk_gt_i32 s3, 0x100f
	v_readfirstlane_b32 s18, v8
	s_cbranch_scc1 .LBB0_124
	s_ashr_i32 s4, s3, 31
	s_lshr_b32 s4, s4, 29
	s_add_i32 s4, s3, s4
	s_ashr_i32 s5, s4, 3
	s_and_b32 s4, s4, -8
	s_sub_i32 s4, s3, s4
	s_cmp_lt_i32 s4, 0
	s_movk_i32 s6, 0x203
	s_cselect_b32 s6, s6, 0x202
	s_mul_i32 s4, s4, s6
	s_add_i32 s4, s4, s5
	s_ashr_i32 s5, s4, 31
	s_lshr_b32 s5, s5, 25
	s_add_i32 s5, s4, s5
	s_ashr_i32 s5, s5, 7
	s_lshl_b32 s6, s5, 3
	s_sub_i32 s7, 0x101, s6
	s_lshl_b32 s5, s5, 7
	s_min_u32 s7, s7, 8
	s_sub_i32 s8, s4, s5
	s_sext_i32_i8 s4, s8
	v_cvt_f32_ubyte0_e32 v1, s7
	v_cvt_f32_i32_e32 v0, s4
	v_rcp_iflag_f32_e32 v2, v1
	s_ashr_i32 s4, s4, 30
	s_or_b32 s9, s4, 1
	v_mul_f32_e32 v2, v0, v2
	v_trunc_f32_e32 v2, v2
	v_fma_f32 v0, -v2, v1, v0
	v_cvt_i32_f32_e32 v2, v2
	v_cmp_ge_f32_e64 s[4:5], |v0|, v1
	s_and_b64 s[4:5], s[4:5], exec
	s_cselect_b32 s4, s9, 0
	v_readfirstlane_b32 s5, v2
	s_add_i32 s4, s5, s4
	s_sext_i32_i8 s81, s4
	s_mul_i32 s4, s4, s7
	s_sub_i32 s4, s8, s4
	s_sext_i32_i8 s4, s4
	s_add_i32 s8, s6, s4
.LBB0_124:
	s_mov_b32 s98, 0
	s_sub_u32 s4, s3, 64
	s_cmpk_lt_u32 s4, 0x1000
	s_cbranch_scc0 .Lmap_smp_first
	s_lshr_b32 s5, s4, 10
	s_and_b32 s9, s4, 7
	s_lshl_b32 s9, s9, 5
	s_lshl_b32 s5, s5, 3
	s_add_u32 s9, s9, s5
	s_bfe_u32 s5, s4, 0x30003
	s_add_u32 s8, s9, s5
	s_bfe_u32 s81, s4, 0x40006
	s_branch .Lmap_done_first
.Lmap_smp_first:
	s_movk_i32 s8, 0x100
	s_sub_u32 s81, s4, 0x1000
.Lmap_done_first:
	s_mov_b64 s[0:1], -1
	v_cndmask_b32_e64 v0, 0, 1, s[0:1]
	s_add_u32 s38, s74, 0x14800000
	v_cmp_ne_u32_e64 s[4:5], 1, v0
	s_addc_u32 s39, s75, 0
	s_andn2_b64 vcc, exec, s[0:1]
	v_writelane_b32 v252, s4, 14
	s_nop 1
	v_writelane_b32 v252, s5, 15
	s_cbranch_vccnz .LBB0_254
	s_mov_b64 s[0:1], 0
	s_cmpk_lt_u32 s81, 0x100
	s_mov_b64 s[4:5], 0
	s_cbranch_scc1 .LBB0_127
	s_ashr_i32 s0, s81, 4
	s_and_b32 s0, s0, -16
	s_ashr_i32 s1, s0, 31
	s_lshl_b64 s[0:1], s[0:1], 7
	s_add_u32 s4, s0, 0xfffff800
	s_addc_u32 s5, s1, -1
	s_movk_i32 s0, 0xf000
	s_mov_b32 s1, -1

.LBB0_131:
.Lsig_check:
	s_cmp_gt_u32 s98, 3
	s_cbranch_scc1 .Lsig_end
	s_mul_i32 s99, s98, 5
	s_add_u32 s99, s99, 6
	s_cmp_eq_u32 s98, 3
	s_cselect_b32 s100, 1, 0
	s_add_u32 s99, s99, s100
	s_cmp_ge_u32 s35, s99
	s_cbranch_scc1 .Lsig_do
	s_cmp_lg_u64 s[4:5], 0
	s_cbranch_scc0 .Lsig_end
.Lsig_do:
	s_waitcnt vmcnt(0)
	s_barrier
	v_readfirstlane_b32 s99, v208
	s_lshr_b32 s99, s99, 6
	s_cmp_lg_u32 s99, 4
	s_cbranch_scc1 .Lsig_skipw
	buffer_wbl2 sc1
	s_waitcnt vmcnt(0)
	s_lshl_b32 s99, s98, 6
	s_add_u32 s99, s99, 0x3800
	v_mov_b32_e32 v253, s99
	v_mov_b32_e32 v254, 1
	s_mov_b64 s[100:101], exec
	s_mov_b64 exec, 1
	global_atomic_add v253, v254, s[74:75]
	s_mov_b64 exec, s[100:101]
.Lsig_skipw:
	s_add_u32 s98, s98, 1
	s_branch .Lsig_check

.LBB0_134:
	s_mul_i32 s4, s35, 0xc0
	s_add_u32 s4, s4, s3
	s_sub_u32 s4, s4, 64
	s_cmpk_lt_u32 s4, 0x1000
	s_cbranch_scc0 .Lmap_smp_next
	s_lshr_b32 s5, s4, 10
	s_and_b32 s9, s4, 7
	s_lshl_b32 s9, s9, 5
	s_lshl_b32 s5, s5, 3
	s_add_u32 s9, s9, s5
	s_bfe_u32 s5, s4, 0x30003
	s_add_u32 s20, s9, s5
	s_bfe_u32 s80, s4, 0x40006
	s_branch .Lmap_done_next
.Lmap_smp_next:
	s_movk_i32 s20, 0x100
	s_sub_u32 s80, s4, 0x1000
.Lmap_done_next:
	s_cmpk_lt_u32 s4, 0x1010
	s_cselect_b64 s[0:1], -1, 0
	s_nop 0
	v_cndmask_b32_e64 v0, 0, 1, s[0:1]
	v_cmp_ne_u32_e64 s[4:5], 1, v0
	s_andn2_b64 vcc, exec, s[0:1]
	s_mov_b64 s[0:1], s[6:7]
	s_cbranch_vccnz .LBB0_138
	s_cmpk_lt_u32 s80, 0x100
	s_mov_b64 s[0:1], 0
	s_cbranch_scc1 .LBB0_137
	s_ashr_i32 s0, s80, 4
	s_and_b32 s0, s0, -16
	s_ashr_i32 s1, s0, 31
	s_lshl_b64 s[0:1], s[0:1], 7
	s_add_u32 s0, s0, 0xfffff800
	s_addc_u32 s1, s1, -1

.LBB0_254:
	s_branch .Lovl_after_p1
	s_waitcnt vmcnt(0)
	s_waitcnt vmcnt(0)
	s_barrier
	s_mov_b64 s[0:1], exec
	v_readlane_b32 s4, v252, 0
	v_readlane_b32 s5, v252, 1
	s_and_b64 s[4:5], s[0:1], s[4:5]
	s_mov_b64 exec, s[4:5]
	s_cbranch_execz .LBB0_306
	s_add_i32 s4, 0, 0x25e00
	v_mov_b32_e32 v0, s4
	s_waitcnt vmcnt(0) expcnt(0) lgkmcnt(0)
	ds_read_b32 v2, v0
	s_add_i32 s4, 0, 0x25e04
	v_mov_b32_e32 v0, s4
	ds_read_b32 v0, v0
	s_waitcnt lgkmcnt(1)
	v_cmp_ne_u32_e32 vcc, 0, v2
	s_cbranch_vccnz .LBB0_270
	v_readlane_b32 s4, v252, 2
	s_mul_i32 s20, s79, s4
	s_add_u32 s4, s74, 0x1000
	s_addc_u32 s5, s75, 0
	s_add_u32 s6, s74, 0x1100
	s_addc_u32 s7, s75, 0
	s_add_u32 s8, s74, 0x1200
	s_addc_u32 s9, s75, 0
	s_add_u32 s12, s74, 0x1300
	s_mul_i32 s20, s20, s78
	s_addc_u32 s13, s75, 0
	s_mov_b32 s21, 1
	v_mov_b32_e32 v16, 0
	s_branch .LBB0_258

.LBB0_306:
	s_or_b64 exec, exec, s[0:1]
	s_branch .Lovl_p2_entry
.Lovl_skip_p1:
	s_add_u32 s38, s74, 0x14800000
	s_addc_u32 s39, s75, 0
	s_mov_b32 s98, 0
	v_writelane_b32 v252, s98, 14
	v_writelane_b32 v252, s98, 15
	s_branch .Lovl_p2_entry
.Lovl_after_p1:
	s_waitcnt vmcnt(0)
	v_mov_b32_e32 v253, 0x3900
	v_readfirstlane_b32 s99, v208
	s_lshr_b32 s99, s99, 6
	s_cmp_lg_u32 s99, 0
	s_cbranch_scc1 .Lovl_c4_nosig
	buffer_wbl2 sc1
	s_waitcnt vmcnt(0)
	v_mov_b32_e32 v254, 1
	s_mov_b64 s[100:101], exec
	s_mov_b64 exec, 1
	global_atomic_add v253, v254, s[74:75]
	s_mov_b64 exec, s[100:101]
.Lovl_c4_nosig:
	s_mov_b32 s99, 0
.Lspin_c4:
	global_load_dword v254, v253, s[74:75] sc1
	s_waitcnt vmcnt(0)
	v_readfirstlane_b32 s100, v254
	s_cmp_ge_u32 s100, 0xc0
	s_cbranch_scc1 .Lspin_done_c4
	s_sleep 8
	s_add_u32 s99, s99, 1
	s_cmp_lt_u32 s99, 0x2000
	s_cbranch_scc1 .Lspin_c4
.Lspin_done_c4:
	buffer_inv sc1
	s_waitcnt vmcnt(0)
.Lovl_p2_entry:
	s_cmpk_gt_i32 s3, 0xbf
	s_waitcnt lgkmcnt(0)
	s_barrier
	s_cbranch_scc0 .LBB0_351
	v_mov_b32_e32 v4, v208
	s_lshl_b32 s1, s3, 3
	v_readfirstlane_b32 s0, v4
	s_ashr_i32 s0, s0, 6
	s_add_i32 s1, s1, s0
	s_add_i32 s18, s1, 0x200
	s_cmpk_gt_i32 s18, 0x31ff
	s_cbranch_scc1 .LBB0_351
	s_lshl_b32 s0, s0, 14
	v_bfe_u32 v102, v4, 5, 1
	v_lshlrev_b32_e32 v0, 2, v4
	v_bfe_u32 v104, v4, 3, 3
	v_lshlrev_b32_e32 v4, 3, v4
	s_add_i32 s19, s76, 0xfffffa00
	s_add_i32 s0, s0, 0
	v_mov_b32_e32 v1, 0
	v_and_b32_e32 v4, 56, v4
	v_readlane_b32 s4, v252, 5
	v_and_b32_e32 v0, 0x7c, v0
	v_mul_u32_u24_e32 v5, 0x84, v102
	v_lshlrev_b32_e32 v34, 1, v4
	v_mov_b32_e32 v35, v1
	v_readlane_b32 s5, v252, 6
	s_cmp_lg_u64 s[56:57], 0
	v_add3_u32 v103, s0, v0, v5
	v_mul_u32_u24_e32 v6, 0x84, v4
	v_lshl_add_u64 v[4:5], s[4:5], 0, v[34:35]
	s_cselect_b64 s[4:5], -1, 0
	s_add_u32 s6, s46, 0x4000
	v_readlane_b32 s8, v252, 9
	s_addc_u32 s7, s47, 0
	v_lshl_add_u64 v[12:13], s[70:71], 0, v[0:1]
	s_mov_b64 s[12:13], 0x1000000
	v_readlane_b32 s9, v252, 10
	v_lshl_add_u64 v[20:21], s[68:69], 0, v[0:1]
	v_lshl_add_u64 v[14:15], v[12:13], 0, s[12:13]
	v_lshl_add_u64 v[16:17], s[8:9], 0, v[34:35]
	s_add_u32 s8, s46, 0x6000
	v_lshl_add_u64 v[22:23], v[20:21], 0, s[12:13]
	v_readlane_b32 s12, v252, 7
	s_addc_u32 s9, s47, 0
	v_readlane_b32 s13, v252, 8
	v_lshlrev_b32_e32 v7, 2, v104
	v_add3_u32 v105, s0, v6, v7
	v_lshl_add_u64 v[24:25], s[12:13], 0, v[34:35]
	s_add_u32 s12, s46, 0x2000
	s_addc_u32 s13, s47, 0
	s_cmp_lg_u64 s[46:47], 0
	s_cselect_b64 s[14:15], -1, 0
	s_lshl_b32 s0, s18, 1
	s_mov_b32 s1, 0
	v_lshl_add_u64 v[2:3], s[66:67], 0, v[0:1]
	v_or_b32_e32 v106, 8, v104
	v_or_b32_e32 v107, 16, v104
	v_or_b32_e32 v108, 24, v104
	v_lshl_add_u64 v[6:7], s[58:59], 0, v[0:1]
	v_lshl_add_u64 v[8:9], s[88:89], 0, v[34:35]
	v_lshl_add_u64 v[10:11], s[60:61], 0, v[0:1]
	v_lshl_add_u64 v[18:19], s[30:31], 0, v[34:35]
	v_lshl_add_u64 v[26:27], s[34:35], 0, v[34:35]
	v_lshl_add_u64 v[28:29], s[54:55], 0, v[0:1]
	v_lshl_add_u64 v[30:31], s[94:95], 0, v[34:35]
	v_lshl_add_u64 v[32:33], s[48:49], 0, v[0:1]
	v_lshl_add_u64 v[34:35], s[10:11], 0, v[34:35]
	s_lshl_b32 s20, s18, 5
	s_lshl_b32 s21, s19, 5
	s_mov_b32 s22, 0x1a000
	s_add_i32 s23, s0, 0x1a000
	s_lshl_b32 s24, s19, 1
	v_add_u32_e32 v109, 0x400, v103
	v_add_u32_e32 v110, 0x800, v103
	v_add_u32_e32 v111, 0xc00, v103
	v_add_u32_e32 v112, 0x1000, v103
	v_add_u32_e32 v113, 0x1400, v103
	v_add_u32_e32 v114, 0x1800, v103
	v_add_u32_e32 v115, 0x1c00, v103
	s_branch .LBB0_311

.LBB0_469:
	s_and_b64 vcc, exec, s[0:1]
	s_cbranch_vccz .LBB0_354
	v_mov_b32_e32 v253, 0x3800
	s_mov_b32 s99, 0

.Lspin_done_g0:
	buffer_inv sc1
	s_waitcnt vmcnt(0)
	v_mov_b32_e32 v36, v208
	s_lshl_b32 s0, s81, 1
	v_readfirstlane_b32 s6, v36
	s_ashr_i32 s7, s6, 6
	s_and_b32 s86, s0, 0x700
	s_lshl_b32 s0, s7, 5
	s_add_i32 s8, 0, 0x13c00
	v_bfe_u32 v38, v36, 4, 2
	s_add_i32 s0, s8, s0
	v_lshl_add_u32 v39, v38, 3, s0
	s_mov_b32 s0, s87
	s_mov_b32 s1, s87
	s_ashr_i32 s36, s70, 3
	v_and_b32_e32 v107, 15, v36
	s_mul_i32 s4, s7, 0x900
	v_mov_b64_e32 v[2:3], s[0:1]
	s_and_b32 s14, s7, 1
	s_lshl_b32 s0, s70, 7
	s_ashr_i32 s37, s36, 31
	v_mad_u32_u24 v0, v107, s83, v39
	s_and_b32 s0, s0, 0x380
	v_lshl_or_b32 v41, s14, 6, v107
	s_add_i32 s1, s4, 0
	s_lshl_b64 s[30:31], s[36:37], 13
	s_barrier
	ds_write_b64 v0, v[2:3]
	ds_write_b64 v0, v[2:3] offset:4352
	ds_write_b64 v0, v[2:3] offset:8704
	ds_write_b64 v0, v[2:3] offset:13056
	ds_write_b64 v0, v[2:3] offset:17408
	ds_write_b64 v0, v[2:3] offset:21760
	ds_write_b64 v0, v[2:3] offset:26112
	ds_write_b64 v0, v[2:3] offset:30464
	v_or_b32_e32 v0, s0, v41
	s_add_i32 s15, s1, 0x1d000
	s_lshl_b32 s0, s0, 1
	s_add_u32 s4, s38, s0
	s_addc_u32 s5, s39, 0
	s_ashr_i32 s16, s6, 7
	v_ashrrev_i32_e32 v24, 4, v36
	s_lshl_b32 s93, s16, 4
	v_bfe_u32 v42, v36, 2, 4
	v_lshlrev_b32_e32 v0, 2, v0
	v_lshlrev_b32_e32 v32, 4, v36
	v_ashrrev_i32_e32 v25, 31, v24
	v_add_u32_e32 v12, 0x200, v36
	v_or_b32_e32 v28, s93, v42
	global_load_dword v108, v0, s[52:53]
	global_load_dword v109, v0, s[52:53] offset:64
	global_load_dword v110, v0, s[52:53] offset:128
	global_load_dword v111, v0, s[52:53] offset:192
	v_and_b32_e32 v96, 0xf0, v32
	v_lshl_add_u64 v[0:1], s[30:31], 0, v[24:25]
	v_ashrrev_i32_e32 v26, 4, v12
	v_ashrrev_i32_e32 v29, 31, v28
	v_lshl_add_u64 v[8:9], s[4:5], 0, v[96:97]
	v_lshlrev_b64 v[0:1], 13, v[0:1]
	v_ashrrev_i32_e32 v27, 31, v26
	v_lshl_add_u64 v[30:31], s[30:31], 0, v[28:29]
	v_lshl_add_u64 v[10:11], v[8:9], 0, v[0:1]
	v_lshl_add_u64 v[12:13], s[30:31], 0, v[26:27]
	v_lshlrev_b64 v[30:31], 13, v[30:31]
	s_mov_b32 s1, s87
	global_load_dwordx4 v[0:3], v[10:11], off
	global_load_dwordx4 v[4:7], v[10:11], off offset:2048
	v_add_co_u32_e32 v10, vcc, s84, v10
	v_lshlrev_b64 v[12:13], 13, v[12:13]
	v_lshl_add_u64 v[30:31], s[38:39], 0, v[30:31]
	v_addc_co_u32_e32 v11, vcc, 0, v11, vcc
	v_lshl_add_u64 v[16:17], v[8:9], 0, v[12:13]
	v_lshl_add_u64 v[30:31], v[30:31], 0, s[0:1]
	s_lshl_b32 s56, s14, 7
	s_mov_b32 s57, s87
	v_add_co_u32_e32 v20, vcc, s84, v16
	v_lshl_add_u64 v[30:31], v[30:31], 0, s[56:57]
	v_and_b32_e32 v32, 48, v32
	v_mov_b32_e32 v33, v97
	v_addc_co_u32_e32 v21, vcc, 0, v17, vcc
	v_lshl_add_u64 v[30:31], v[30:31], 0, v[32:33]
	v_lshl_add_u64 v[34:35], v[30:31], 0, s[58:59]
	v_add_co_u32_e32 v30, vcc, s84, v30
	global_load_dwordx4 v[8:11], v[10:11], off
	s_nop 0
	global_load_dwordx4 v[12:15], v[16:17], off
	v_addc_co_u32_e32 v31, vcc, 0, v31, vcc
	global_load_dwordx4 v[16:19], v[16:17], off offset:2048
	s_nop 0
	global_load_dwordx4 v[20:23], v[20:21], off
	s_nop 0
	global_load_dwordx4 v[68:71], v[30:31], off offset:2048
	global_load_dwordx4 v[56:59], v[34:35], off offset:64
	s_and_b32 s0, s6, 0x3fffff80
	v_and_b32_e32 v37, 0x7f, v36
	s_add_i32 s1, 0, 0x1c400
	s_lshl_b32 s0, s0, 2
	s_add_i32 s0, s1, s0
	v_lshlrev_b32_e32 v33, 2, v37
	v_add_u32_e32 v30, 0, v96
	v_add_u32_e32 v31, s85, v96
	v_add_u32_e32 v96, s0, v33
	s_lshl_b32 s0, s16, 5
	s_add_i32 s0, s0, 0
	v_mul_u32_u24_e32 v34, 0x48, v37
	s_cmpk_lt_u32 s6, 0x80
	v_and_b32_e32 v115, 48, v36
	v_add_u32_e32 v112, s1, v33
	v_lshl_add_u32 v114, v34, 1, s0
	s_cselect_b64 s[0:1], -1, 0
	v_mov_b32_e32 v44, s8
	v_add_u32_e32 v45, s8, v115
	s_lshl_b32 s8, s16, 6
	s_add_i32 s8, s8, 0
	s_add_i32 s92, 0, 0x1cc00
	s_andn2_b32 s6, s6, 63
	v_mul_lo_u32 v48, v24, s83
	s_add_i32 s8, s8, 0x1ce00
	s_lshl_b32 s9, s14, 8
	v_add_u32_e32 v118, s92, v33
	s_add_i32 s92, s92, s6
	v_add_u32_e32 v119, v30, v48
	v_add_u32_e32 v120, v31, v48
	v_mul_lo_u32 v48, v26, s83
	s_mul_i32 s6, s16, 0x880
	s_lshl_b32 s17, s14, 1
	s_add_i32 s91, s8, s9
	s_ashr_i32 vcc_lo, s93, 31
	s_lshl_b32 s57, s7, 4
	v_add_u32_e32 v121, v30, v48
	v_or_b32_e32 v30, s6, v37
	s_addk_i32 s6, 0x110
	v_lshlrev_b32_e32 v30, 1, v30
	s_cmp_gt_i32 s16, 0
	v_add_u32_e32 v123, 0, v30
	v_add_u32_e32 v124, s85, v30
	v_add_u32_e32 v30, s6, v37
	s_cselect_b64 s[6:7], -1, 0
	s_cmp_gt_i32 s16, 1
	v_add_u32_e32 v117, s8, v115
	s_cselect_b64 s[8:9], -1, 0
	s_cmp_gt_i32 s16, 2
	s_cselect_b64 s[10:11], -1, 0
	s_cmp_gt_i32 s16, 3
	v_lshlrev_b32_e32 v113, 2, v38
	s_cselect_b64 s[12:13], -1, 0
	s_cmp_le_i32 s17, s16
	v_or_b32_e32 v36, s93, v113
	v_lshl_add_u32 v126, v30, 1, s85
	s_cselect_b64 s[34:35], -1, 0
	v_lshl_or_b32 v30, s14, 5, v107
	s_cmp_lt_i32 s17, s16
	v_add_u32_e32 v116, 0, v115
	v_mul_u32_u24_e32 v33, 0x90, v42
	v_add_u32_e32 v122, v31, v48
	v_or_b32_e32 v31, 1, v36
	v_or_b32_e32 v49, 2, v36
	v_or_b32_e32 v50, 3, v36
	s_cselect_b64 s[96:97], -1, 0
	v_or_b32_e32 v51, 16, v30
	v_mul_u32_u24_e32 v141, 0x90, v107
	s_mov_b32 s14, 0xd000
	s_add_u32 s30, s93, s30
	v_lshl_add_u32 v46, v107, 1, s15
	v_mul_u32_u24_e32 v37, 0x110, v30
	v_mul_lo_u32 v48, v36, s88
	v_add3_u32 v140, s15, v33, v32
	v_add3_u32 v142, v116, v141, s14
	v_lshl_add_u32 v33, v30, 1, s89
	v_cmp_gt_i32_e64 s[14:15], v30, v36
	v_cmp_gt_i32_e64 s[16:17], v30, v31
	v_cmp_gt_i32_e64 s[18:19], v30, v49
	v_cmp_gt_i32_e64 s[20:21], v30, v50
	v_lshlrev_b32_e32 v30, 1, v51
	s_addc_u32 s31, vcc_lo, s31
	v_add3_u32 v143, s89, v48, v30
	v_cmp_gt_i32_e64 s[24:25], v51, v31
	v_or_b32_e32 v30, s30, v42
	v_mov_b32_e32 v31, s31
	s_lshl_b64 s[30:31], s[36:37], 26
	v_lshlrev_b64 v[28:29], 13, v[28:29]
	v_lshl_add_u64 v[28:29], s[30:31], 0, v[28:29]
	v_or3_b32 v28, v28, s56, v32
	v_lshlrev_b64 v[24:25], 13, v[24:25]
	v_lshl_add_u64 v[100:101], s[74:75], 0, v[28:29]
	v_lshl_add_u64 v[24:25], s[30:31], 0, v[24:25]
	v_lshlrev_b32_e32 v28, 4, v107
	v_or_b32_e32 v24, v24, v28
	v_lshl_add_u64 v[102:103], s[74:75], 0, v[24:25]
	v_lshlrev_b64 v[24:25], 13, v[26:27]
	v_or_b32_e32 v34, s93, v107
	v_or_b32_e32 v47, s57, v107
	v_lshl_add_u64 v[24:25], s[30:31], 0, v[24:25]
	v_mul_lo_u32 v35, v34, s83
	v_mul_lo_u32 v34, v34, s88
	v_mad_u32_u24 v43, v41, s88, 0
	v_mad_u32_u24 v44, v41, s83, v44
	v_or_b32_e32 v41, 16, v41
	v_mul_lo_u32 v47, v47, s88
	v_lshlrev_b64 v[30:31], 11, v[30:31]
	v_or_b32_e32 v24, v24, v28
	v_mul_u32_u24_e32 v40, 0x110, v107
	v_add_u32_e32 v35, 0, v35
	v_add_u32_e32 v34, s89, v34
	v_add_u32_e32 v47, 0, v47
	v_mul_u32_u24_e32 v52, 0x90, v41
	v_mul_u32_u24_e32 v41, 0x110, v41
	v_mul_u32_u24_e32 v38, 0x240, v38
	v_or3_b32 v30, v30, s56, v32
	v_lshl_add_u64 v[104:105], s[74:75], 0, v[24:25]
	v_mov_b32_e32 v24, 0
	s_waitcnt vmcnt(1)
	v_mov_b64_e32 v[60:61], v[68:69]
	s_waitcnt vmcnt(0)
	v_mov_b64_e32 v[66:67], v[58:59]
	s_movk_i32 s71, 0x7f
	v_cmp_eq_u32_e64 s[4:5], 0, v107
	v_add_u32_e32 v125, 0x110, v124
	v_add_u32_e32 v127, 0x330, v124
	v_add_u32_e32 v128, 0x440, v124
	v_add_u32_e32 v129, 0x550, v124
	v_add_u32_e32 v130, 0x660, v124
	v_add_u32_e32 v131, 0x770, v124
	v_add_u32_e32 v132, 0x880, v124
	v_add_u32_e32 v133, 0x990, v124
	v_add_u32_e32 v134, 0xaa0, v124
	v_add_u32_e32 v135, 0xbb0, v124
	v_add_u32_e32 v136, 0xcc0, v124
	v_add_u32_e32 v137, 0xdd0, v124
	v_add_u32_e32 v138, 0xee0, v124
	v_add_u32_e32 v139, 0xff0, v124
	v_cmp_gt_i32_e64 s[22:23], v51, v36
	v_add_u32_e32 v144, 0x90, v143
	v_cmp_gt_i32_e64 s[26:27], v51, v49
	v_add_u32_e32 v145, 0x120, v143
	v_cmp_gt_i32_e64 s[28:29], v51, v50
	v_add_u32_e32 v146, 0x1b0, v143
	v_lshl_add_u64 v[98:99], s[74:75], 0, v[30:31]
	v_add_u32_e32 v147, v33, v48
	v_add_u32_e32 v148, v34, v115
	v_add_u32_e32 v149, v43, v115
	v_add_u32_e32 v150, v44, v115
	v_add_u32_e32 v151, v116, v52
	v_add_u32_e32 v152, v45, v41
	v_add_u32_e32 v153, v46, v38
	v_add_u32_e32 v154, v47, v115
	v_add_u32_e32 v155, v39, v40
	v_add_u32_e32 v156, v35, v115
	v_add_u32_e32 v157, v116, v37
	v_mov_b32_e32 v25, v24
	v_mov_b32_e32 v26, v24
	v_mov_b32_e32 v27, v24
	v_mov_b32_e32 v32, v24
	v_mov_b32_e32 v33, v24
	v_mov_b32_e32 v34, v24
	v_mov_b32_e32 v35, v24
	v_mov_b32_e32 v40, v24
	v_mov_b32_e32 v41, v24
	v_mov_b32_e32 v42, v24
	v_mov_b32_e32 v43, v24
	v_mov_b32_e32 v44, v24
	v_mov_b32_e32 v45, v24
	v_mov_b32_e32 v46, v24
	v_mov_b32_e32 v47, v24
	v_mov_b32_e32 v28, v24
	v_mov_b32_e32 v29, v24
	v_mov_b32_e32 v30, v24
	v_mov_b32_e32 v31, v24
	v_mov_b32_e32 v36, v24
	v_mov_b32_e32 v37, v24
	v_mov_b32_e32 v38, v24
	v_mov_b32_e32 v39, v24
	v_mov_b32_e32 v48, v24
	v_mov_b32_e32 v49, v24
	v_mov_b32_e32 v50, v24
	v_mov_b32_e32 v51, v24
	v_mov_b32_e32 v52, v24
	v_mov_b32_e32 v53, v24
	v_mov_b32_e32 v54, v24
	v_mov_b32_e32 v55, v24
	v_mov_b64_e32 v[62:63], v[70:71]
	v_mov_b64_e32 v[64:65], v[56:57]
	s_branch .LBB0_472

.LBB0_472:
	s_and_b32 s98, s71, 31
	s_cmp_lg_u32 s98, 0
	s_cbranch_scc1 .Lhw_skip
	s_cmp_eq_u32 s71, 0
	s_cbranch_scc1 .Lhw_skip
	s_lshr_b32 s98, s71, 5
	s_sub_u32 s98, 4, s98
	s_lshl_b32 s98, s98, 6
	s_add_u32 s98, s98, 0x3800
	v_mov_b32_e32 v253, s98
	s_mov_b32 s99, 0

	.amdhsa_kernel _Z8yoco_fwd4Args
		.amdhsa_group_segment_fixed_size 0
		.amdhsa_private_segment_fixed_size 0
		.amdhsa_kernarg_size 416
		.amdhsa_user_sgpr_count 2
		.amdhsa_user_sgpr_dispatch_ptr 0
		.amdhsa_user_sgpr_queue_ptr 0
		.amdhsa_user_sgpr_kernarg_segment_ptr 1
		.amdhsa_user_sgpr_dispatch_id 0
		.amdhsa_user_sgpr_kernarg_preload_length 0
		.amdhsa_user_sgpr_kernarg_preload_offset 0
		.amdhsa_user_sgpr_private_segment_size 0
		.amdhsa_uses_dynamic_stack 0
		.amdhsa_enable_private_segment 0
		.amdhsa_system_sgpr_workgroup_id_x 1
		.amdhsa_system_sgpr_workgroup_id_y 0
		.amdhsa_system_sgpr_workgroup_id_z 0
		.amdhsa_system_sgpr_workgroup_info 0
		.amdhsa_system_vgpr_workitem_id 2
		.amdhsa_next_free_vgpr 255
		.amdhsa_next_free_sgpr 102
		.amdhsa_accum_offset 256
		.amdhsa_reserve_vcc 1
		.amdhsa_float_round_mode_32 0
		.amdhsa_float_round_mode_16_64 0
		.amdhsa_float_denorm_mode_32 3
		.amdhsa_float_denorm_mode_16_64 3
		.amdhsa_dx10_clamp 1
		.amdhsa_ieee_mode 1
		.amdhsa_fp16_overflow 0
		.amdhsa_tg_split 0
		.amdhsa_exception_fp_ieee_invalid_op 0
		.amdhsa_exception_fp_denorm_src 0
		.amdhsa_exception_fp_ieee_div_zero 0
		.amdhsa_exception_fp_ieee_overflow 0
		.amdhsa_exception_fp_ieee_underflow 0
		.amdhsa_exception_fp_ieee_inexact 0
		.amdhsa_exception_int_div_zero 0
	.end_amdhsa_kernel

amdhsa.kernels:
  - .agpr_count:     0
    .args:
      - .offset:         0
        .size:           160
        .value_kind:     by_value
      - .offset:         160
        .size:           4
        .value_kind:     hidden_block_count_x
      - .offset:         164
        .size:           4
        .value_kind:     hidden_block_count_y
      - .offset:         168
        .size:           4
        .value_kind:     hidden_block_count_z
      - .offset:         172
        .size:           2
        .value_kind:     hidden_group_size_x
      - .offset:         174
        .size:           2
        .value_kind:     hidden_group_size_y
      - .offset:         176
        .size:           2
        .value_kind:     hidden_group_size_z
      - .offset:         178
        .size:           2
        .value_kind:     hidden_remainder_x
      - .offset:         180
        .size:           2
        .value_kind:     hidden_remainder_y
      - .offset:         182
        .size:           2
        .value_kind:     hidden_remainder_z
      - .offset:         200
        .size:           8
        .value_kind:     hidden_global_offset_x
      - .offset:         208
        .size:           8
        .value_kind:     hidden_global_offset_y
      - .offset:         216
        .size:           8
        .value_kind:     hidden_global_offset_z
      - .offset:         224
        .size:           2
        .value_kind:     hidden_grid_dims
      - .offset:         248
        .size:           8
        .value_kind:     hidden_multigrid_sync_arg
      - .offset:         280
        .size:           4
        .value_kind:     hidden_dynamic_lds_size
    .group_segment_fixed_size: 0
    .kernarg_segment_align: 8
    .kernarg_segment_size: 416
    .language:       OpenCL C
    .language_version:
      - 2
      - 0
    .max_flat_workgroup_size: 512
    .name:           _Z8yoco_fwd4Args
    .private_segment_fixed_size: 0
    .sgpr_count:     108
    .sgpr_spill_count: 22
    .symbol:         _Z8yoco_fwd4Args.kd
    .uniform_work_group_size: 1
    .uses_dynamic_stack: false
    .vgpr_count:     255
    .vgpr_spill_count: 0
    .wavefront_size: 64
